# attention key-tile loop: waves 4-7 start 1280 cycles later than their SIMD partners (stagger so matrix and softmax segments of partner waves overlap)
# speedup vs baseline: 1.0017x; 1.0017x over previous
.Lattn0_ld9:
	s_or_b64 exec, exec, s[0:1]
	s_waitcnt vmcnt(0)
	s_barrier
	ds_write_b128 v189, v[10:13]
	ds_write_b128 v190, v[14:17]
	ds_write_b128 v191, v[18:21]
	ds_write_b128 v192, v[22:25]
	ds_write_b128 v193, v[26:29]
	ds_write_b16 v180, v30 offset:46080
	ds_write_b16_d16_hi v180, v30 offset:46736
	ds_write_b16 v180, v31 offset:47392
	ds_write_b16_d16_hi v180, v31 offset:48048
	ds_write_b16 v180, v32 offset:48704
	ds_write_b16_d16_hi v180, v32 offset:49360
	ds_write_b16 v180, v33 offset:50016
	ds_write_b16_d16_hi v180, v33 offset:50672
	ds_write_b16 v180, v34 offset:46208
	ds_write_b16_d16_hi v180, v34 offset:46864
	ds_write_b16 v180, v35 offset:47520
	ds_write_b16_d16_hi v180, v35 offset:48176
	ds_write_b16 v180, v36 offset:48832
	ds_write_b16_d16_hi v180, v36 offset:49488
	ds_write_b16 v180, v37 offset:50144
	ds_write_b16_d16_hi v180, v37 offset:50800
	ds_write_b16 v180, v38 offset:46336
	ds_write_b16_d16_hi v180, v38 offset:46992
	ds_write_b16 v180, v39 offset:47648
	ds_write_b16_d16_hi v180, v39 offset:48304
	ds_write_b16 v180, v40 offset:48960
	ds_write_b16_d16_hi v180, v40 offset:49616
	ds_write_b16 v180, v41 offset:50272
	ds_write_b16_d16_hi v180, v41 offset:50928
	ds_write_b16 v180, v42 offset:46464
	ds_write_b16_d16_hi v180, v42 offset:47120
	ds_write_b16 v180, v43 offset:47776
	ds_write_b16_d16_hi v180, v43 offset:48432
	ds_write_b16 v180, v44 offset:49088
	ds_write_b16_d16_hi v180, v44 offset:49744
	ds_write_b16 v180, v45 offset:50400
	ds_write_b16_d16_hi v180, v45 offset:51056
	ds_write_b16 v180, v46 offset:46592
	ds_write_b16_d16_hi v180, v46 offset:47248
	ds_write_b16 v180, v47 offset:47904
	ds_write_b16_d16_hi v180, v47 offset:48560
	ds_write_b16 v180, v48 offset:49216
	ds_write_b16_d16_hi v180, v48 offset:49872
	ds_write_b16 v180, v49 offset:50528
	ds_write_b16_d16_hi v180, v49 offset:51184
	v_mov_b32_e32 v14, v0
	v_mov_b32_e32 v15, v0
	v_mov_b32_e32 v1, v0
	v_mov_b32_e32 v2, v0
	v_mov_b32_e32 v3, v0
	v_mov_b32_e32 v4, v0
	v_mov_b32_e32 v5, v0
	v_mov_b32_e32 v6, v0
	v_mov_b32_e32 v7, v0
	v_mov_b32_e32 v8, v0
	v_mov_b32_e32 v9, v0
	v_mov_b32_e32 v10, v0
	v_mov_b32_e32 v11, v0
	v_mov_b32_e32 v12, v0
	v_mov_b32_e32 v13, v0
	v_mov_b64_e32 v[64:65], v[14:15]
	v_mov_b64_e32 v[32:33], v[14:15]
	v_mov_b64_e32 v[48:49], v[14:15]
	s_and_b32 s0, s2, 0xffffffc0
	v_mov_b64_e32 v[62:63], v[12:13]
	v_mov_b64_e32 v[60:61], v[10:11]
	v_mov_b64_e32 v[58:59], v[8:9]
	v_mov_b64_e32 v[56:57], v[6:7]
	v_mov_b64_e32 v[54:55], v[4:5]
	v_mov_b64_e32 v[52:53], v[2:3]
	v_mov_b64_e32 v[50:51], v[0:1]
	v_mov_b64_e32 v[30:31], v[12:13]
	v_mov_b64_e32 v[28:29], v[10:11]
	v_mov_b64_e32 v[26:27], v[8:9]
	v_mov_b64_e32 v[24:25], v[6:7]
	v_mov_b64_e32 v[22:23], v[4:5]
	v_mov_b64_e32 v[20:21], v[2:3]
	v_mov_b64_e32 v[18:19], v[0:1]
	v_mov_b64_e32 v[46:47], v[12:13]
	v_mov_b64_e32 v[44:45], v[10:11]
	v_mov_b64_e32 v[42:43], v[8:9]
	v_mov_b64_e32 v[40:41], v[6:7]
	v_mov_b64_e32 v[38:39], v[4:5]
	v_mov_b64_e32 v[36:37], v[2:3]
	v_mov_b64_e32 v[34:35], v[0:1]
	v_mov_b64_e32 v[16:17], v[14:15]
	s_sub_i32 s72, s0, s4
	v_mov_b32_e32 v199, 1.0
	v_mov_b32_e32 v196, v187
	v_mov_b32_e32 v197, v186
	v_mov_b32_e32 v198, v185
	v_mov_b64_e32 v[14:15], v[12:13]
	v_mov_b64_e32 v[12:13], v[10:11]
	v_mov_b64_e32 v[10:11], v[8:9]
	v_mov_b64_e32 v[8:9], v[6:7]
	v_mov_b64_e32 v[6:7], v[4:5]
	v_mov_b64_e32 v[4:5], v[2:3]
	v_mov_b64_e32 v[2:3], v[0:1]
	v_mov_b32_e32 v1, 1.0
	v_mov_b32_e32 v200, v202
	s_mov_b32 s78, 0
	s_waitcnt lgkmcnt(0)
	s_barrier
	v_readlane_b32 s48, v254, 0
	v_readlane_b32 s49, v254, 1
	v_readlane_b32 s50, v254, 2
	v_readlane_b32 s51, v254, 3
	v_readlane_b32 s58, v254, 10
	v_readlane_b32 s59, v254, 11
	v_readlane_b32 s52, v254, 4
	v_readlane_b32 s53, v254, 5
	v_readlane_b32 s54, v254, 6
	v_readlane_b32 s55, v254, 7
	v_readlane_b32 s56, v254, 8
	v_readlane_b32 s57, v254, 9
	v_readlane_b32 s60, v254, 12
	v_readlane_b32 s61, v254, 13
	v_readlane_b32 s62, v254, 14
	v_readlane_b32 s63, v254, 15
	v_readfirstlane_b32 s4, v210
	s_nop 3
	s_cmp_lt_u32 s4, 0x100
	s_cbranch_scc1 .Lattn_stag0
	s_sleep 20
.Lattn_stag0:
.LBB0_628:
	ds_read_b128 v[66:69], v198
	ds_read_b128 v[204:207], v198 offset:32
	s_add_i32 s6, s72, 0xffffff80
	s_and_b32 s0, s78, 3
	s_cmp_eq_u32 s0, 0
	s_cselect_b64 s[0:1], -1, 0
	s_cmp_ge_u32 s6, s71
	s_cselect_b64 s[4:5], -1, 0
	s_or_b64 s[94:95], s[0:1], s[4:5]
	s_waitcnt lgkmcnt(1)
	v_mfma_f32_32x32x16_bf16 v[114:129], v[66:69], v[130:133], 0
	s_cmp_gt_i32 s6, -1
	s_mov_b64 s[0:1], -1
	s_cselect_b64 s[92:93], -1, 0
	s_and_b64 vcc, exec, s[94:95]
	v_mfma_f32_32x32x16_bf16 v[82:97], v[66:69], v[146:149], 0
	ds_read_b128 v[66:69], v198 offset:4608
	s_waitcnt lgkmcnt(1)
	v_mfma_f32_32x32x16_bf16 v[114:129], v[204:207], v[134:137], v[114:129]
	v_mfma_f32_32x32x16_bf16 v[82:97], v[204:207], v[150:153], v[82:97]
	ds_read_b128 v[204:207], v198 offset:4640
	s_waitcnt lgkmcnt(1)
	v_mfma_f32_32x32x16_bf16 v[98:113], v[66:69], v[130:133], 0
	v_mfma_f32_32x32x16_bf16 v[66:81], v[66:69], v[146:149], 0
	s_waitcnt lgkmcnt(0)
	v_mfma_f32_32x32x16_bf16 v[98:113], v[204:207], v[134:137], v[98:113]
	v_mfma_f32_32x32x16_bf16 v[66:81], v[204:207], v[150:153], v[66:81]
	ds_read_b128 v[204:207], v198 offset:64
	s_waitcnt lgkmcnt(0)
	v_mfma_f32_32x32x16_bf16 v[114:129], v[204:207], v[138:141], v[114:129]
	v_mfma_f32_32x32x16_bf16 v[82:97], v[204:207], v[154:157], v[82:97]
	ds_read_b128 v[204:207], v198 offset:4672
	s_waitcnt lgkmcnt(0)
	v_mfma_f32_32x32x16_bf16 v[98:113], v[204:207], v[138:141], v[98:113]
	v_mfma_f32_32x32x16_bf16 v[66:81], v[204:207], v[154:157], v[66:81]
	ds_read_b128 v[204:207], v198 offset:96
	s_waitcnt lgkmcnt(0)
	v_mfma_f32_32x32x16_bf16 v[114:129], v[204:207], v[142:145], v[114:129]
	v_mfma_f32_32x32x16_bf16 v[82:97], v[204:207], v[158:161], v[82:97]
	ds_read_b128 v[204:207], v198 offset:4704
	s_waitcnt lgkmcnt(0)
	v_mfma_f32_32x32x16_bf16 v[98:113], v[204:207], v[142:145], v[98:113]
	v_mfma_f32_32x32x16_bf16 v[66:81], v[204:207], v[158:161], v[66:81]
	s_cbranch_vccnz .LBB0_630
	s_mov_b32 s0, 0xf149f2ca
	s_nop 4
	v_max3_f32 v201, v114, s0, v115
	v_max3_f32 v201, v201, v116, v117
	v_max3_f32 v201, v201, v118, v119
	v_max3_f32 v201, v201, v120, v121
	v_max3_f32 v201, v201, v122, v123
	v_max3_f32 v201, v201, v124, v125
	v_max3_f32 v201, v201, v126, v127
	v_max3_f32 v201, v201, v128, v129
	v_max3_f32 v201, v201, v98, v99
	v_max3_f32 v201, v201, v100, v101
	v_max3_f32 v201, v201, v102, v103
	v_max3_f32 v201, v201, v104, v105
	v_max3_f32 v201, v201, v106, v107
	v_max3_f32 v201, v201, v108, v109
	v_max3_f32 v201, v201, v110, v111
	v_max3_f32 v201, v201, v112, v113
	s_mov_b64 s[0:1], 0

.Lattn1_ld9:
	s_or_b64 exec, exec, s[0:1]
	s_waitcnt vmcnt(0)
	s_barrier
	ds_write_b128 v189, v[10:13]
	ds_write_b128 v190, v[14:17]
	ds_write_b128 v191, v[18:21]
	ds_write_b128 v192, v[22:25]
	ds_write_b128 v193, v[26:29]
	ds_write_b16 v180, v30 offset:46080
	ds_write_b16_d16_hi v180, v30 offset:46736
	ds_write_b16 v180, v31 offset:47392
	ds_write_b16_d16_hi v180, v31 offset:48048
	ds_write_b16 v180, v32 offset:48704
	ds_write_b16_d16_hi v180, v32 offset:49360
	ds_write_b16 v180, v33 offset:50016
	ds_write_b16_d16_hi v180, v33 offset:50672
	ds_write_b16 v180, v34 offset:46208
	ds_write_b16_d16_hi v180, v34 offset:46864
	ds_write_b16 v180, v35 offset:47520
	ds_write_b16_d16_hi v180, v35 offset:48176
	ds_write_b16 v180, v36 offset:48832
	ds_write_b16_d16_hi v180, v36 offset:49488
	ds_write_b16 v180, v37 offset:50144
	ds_write_b16_d16_hi v180, v37 offset:50800
	ds_write_b16 v180, v38 offset:46336
	ds_write_b16_d16_hi v180, v38 offset:46992
	ds_write_b16 v180, v39 offset:47648
	ds_write_b16_d16_hi v180, v39 offset:48304
	ds_write_b16 v180, v40 offset:48960
	ds_write_b16_d16_hi v180, v40 offset:49616
	ds_write_b16 v180, v41 offset:50272
	ds_write_b16_d16_hi v180, v41 offset:50928
	ds_write_b16 v180, v42 offset:46464
	ds_write_b16_d16_hi v180, v42 offset:47120
	ds_write_b16 v180, v43 offset:47776
	ds_write_b16_d16_hi v180, v43 offset:48432
	ds_write_b16 v180, v44 offset:49088
	ds_write_b16_d16_hi v180, v44 offset:49744
	ds_write_b16 v180, v45 offset:50400
	ds_write_b16_d16_hi v180, v45 offset:51056
	ds_write_b16 v180, v46 offset:46592
	ds_write_b16_d16_hi v180, v46 offset:47248
	ds_write_b16 v180, v47 offset:47904
	ds_write_b16_d16_hi v180, v47 offset:48560
	ds_write_b16 v180, v48 offset:49216
	ds_write_b16_d16_hi v180, v48 offset:49872
	ds_write_b16 v180, v49 offset:50528
	ds_write_b16_d16_hi v180, v49 offset:51184
	v_mov_b32_e32 v14, v0
	v_mov_b32_e32 v15, v0
	v_mov_b32_e32 v1, v0
	v_mov_b32_e32 v2, v0
	v_mov_b32_e32 v3, v0
	v_mov_b32_e32 v4, v0
	v_mov_b32_e32 v5, v0
	v_mov_b32_e32 v6, v0
	v_mov_b32_e32 v7, v0
	v_mov_b32_e32 v8, v0
	v_mov_b32_e32 v9, v0
	v_mov_b32_e32 v10, v0
	v_mov_b32_e32 v11, v0
	v_mov_b32_e32 v12, v0
	v_mov_b32_e32 v13, v0
	v_mov_b64_e32 v[64:65], v[14:15]
	v_mov_b64_e32 v[32:33], v[14:15]
	v_mov_b64_e32 v[48:49], v[14:15]
	s_and_b32 s0, s95, 0xffffffc0
	v_mov_b64_e32 v[62:63], v[12:13]
	v_mov_b64_e32 v[60:61], v[10:11]
	v_mov_b64_e32 v[58:59], v[8:9]
	v_mov_b64_e32 v[56:57], v[6:7]
	v_mov_b64_e32 v[54:55], v[4:5]
	v_mov_b64_e32 v[52:53], v[2:3]
	v_mov_b64_e32 v[50:51], v[0:1]
	v_mov_b64_e32 v[30:31], v[12:13]
	v_mov_b64_e32 v[28:29], v[10:11]
	v_mov_b64_e32 v[26:27], v[8:9]
	v_mov_b64_e32 v[24:25], v[6:7]
	v_mov_b64_e32 v[22:23], v[4:5]
	v_mov_b64_e32 v[20:21], v[2:3]
	v_mov_b64_e32 v[18:19], v[0:1]
	v_mov_b64_e32 v[46:47], v[12:13]
	v_mov_b64_e32 v[44:45], v[10:11]
	v_mov_b64_e32 v[42:43], v[8:9]
	v_mov_b64_e32 v[40:41], v[6:7]
	v_mov_b64_e32 v[38:39], v[4:5]
	v_mov_b64_e32 v[36:37], v[2:3]
	v_mov_b64_e32 v[34:35], v[0:1]
	v_mov_b64_e32 v[16:17], v[14:15]
	s_sub_i32 s72, s0, s4
	v_mov_b32_e32 v199, 1.0
	v_mov_b32_e32 v196, v187
	v_mov_b32_e32 v197, v186
	v_mov_b32_e32 v198, v185
	v_mov_b64_e32 v[14:15], v[12:13]
	v_mov_b64_e32 v[12:13], v[10:11]
	v_mov_b64_e32 v[10:11], v[8:9]
	v_mov_b64_e32 v[8:9], v[6:7]
	v_mov_b64_e32 v[6:7], v[4:5]
	v_mov_b64_e32 v[4:5], v[2:3]
	v_mov_b64_e32 v[2:3], v[0:1]
	v_mov_b32_e32 v1, 1.0
	v_mov_b32_e32 v200, v202
	s_mov_b32 s94, 0
	s_waitcnt lgkmcnt(0)
	s_barrier
	v_readlane_b32 s48, v254, 0
	v_readlane_b32 s49, v254, 1
	v_readlane_b32 s50, v254, 2
	v_readlane_b32 s51, v254, 3
	v_readlane_b32 s54, v254, 6
	v_readlane_b32 s55, v254, 7
	v_readlane_b32 s58, v254, 10
	v_readlane_b32 s59, v254, 11
	v_readlane_b32 s52, v254, 4
	v_readlane_b32 s53, v254, 5
	v_readlane_b32 s56, v254, 8
	v_readlane_b32 s57, v254, 9
	v_readlane_b32 s60, v254, 12
	v_readlane_b32 s61, v254, 13
	v_readlane_b32 s62, v254, 14
	v_readlane_b32 s63, v254, 15
	v_readfirstlane_b32 s4, v210
	s_nop 3
	s_cmp_lt_u32 s4, 0x100
	s_cbranch_scc1 .Lattn_stag1
	s_sleep 20
.Lattn_stag1:
.LBB0_2210:
	ds_read_b128 v[66:69], v198
	ds_read_b128 v[204:207], v198 offset:32
	s_add_i32 s6, s72, 0xffffff80
	s_and_b32 s0, s94, 3
	s_cmp_eq_u32 s0, 0
	s_cselect_b64 s[0:1], -1, 0
	s_cmp_ge_u32 s6, s71
	s_cselect_b64 s[4:5], -1, 0
	s_or_b64 s[92:93], s[0:1], s[4:5]
	s_waitcnt lgkmcnt(1)
	v_mfma_f32_32x32x16_bf16 v[114:129], v[66:69], v[130:133], 0
	s_cmp_gt_i32 s6, -1
	s_mov_b64 s[0:1], -1
	s_cselect_b64 s[86:87], -1, 0
	s_and_b64 vcc, exec, s[92:93]
	v_mfma_f32_32x32x16_bf16 v[82:97], v[66:69], v[146:149], 0
	ds_read_b128 v[66:69], v198 offset:4608
	s_waitcnt lgkmcnt(1)
	v_mfma_f32_32x32x16_bf16 v[114:129], v[204:207], v[134:137], v[114:129]
	v_mfma_f32_32x32x16_bf16 v[82:97], v[204:207], v[150:153], v[82:97]
	ds_read_b128 v[204:207], v198 offset:4640
	s_waitcnt lgkmcnt(1)
	v_mfma_f32_32x32x16_bf16 v[98:113], v[66:69], v[130:133], 0
	v_mfma_f32_32x32x16_bf16 v[66:81], v[66:69], v[146:149], 0
	s_waitcnt lgkmcnt(0)
	v_mfma_f32_32x32x16_bf16 v[98:113], v[204:207], v[134:137], v[98:113]
	v_mfma_f32_32x32x16_bf16 v[66:81], v[204:207], v[150:153], v[66:81]
	ds_read_b128 v[204:207], v198 offset:64
	s_waitcnt lgkmcnt(0)
	v_mfma_f32_32x32x16_bf16 v[114:129], v[204:207], v[138:141], v[114:129]
	v_mfma_f32_32x32x16_bf16 v[82:97], v[204:207], v[154:157], v[82:97]
	ds_read_b128 v[204:207], v198 offset:4672
	s_waitcnt lgkmcnt(0)
	v_mfma_f32_32x32x16_bf16 v[98:113], v[204:207], v[138:141], v[98:113]
	v_mfma_f32_32x32x16_bf16 v[66:81], v[204:207], v[154:157], v[66:81]
	ds_read_b128 v[204:207], v198 offset:96
	s_waitcnt lgkmcnt(0)
	v_mfma_f32_32x32x16_bf16 v[114:129], v[204:207], v[142:145], v[114:129]
	v_mfma_f32_32x32x16_bf16 v[82:97], v[204:207], v[158:161], v[82:97]
	ds_read_b128 v[204:207], v198 offset:4704
	s_waitcnt lgkmcnt(0)
	v_mfma_f32_32x32x16_bf16 v[98:113], v[204:207], v[142:145], v[98:113]
	v_mfma_f32_32x32x16_bf16 v[66:81], v[204:207], v[158:161], v[66:81]
	s_cbranch_vccnz .LBB0_2212
	s_mov_b32 s0, 0xf149f2ca
	s_nop 4
	v_max3_f32 v201, v114, s0, v115
	v_max3_f32 v201, v201, v116, v117
	v_max3_f32 v201, v201, v118, v119
	v_max3_f32 v201, v201, v120, v121
	v_max3_f32 v201, v201, v122, v123
	v_max3_f32 v201, v201, v124, v125
	v_max3_f32 v201, v201, v126, v127
	v_max3_f32 v201, v201, v128, v129
	v_max3_f32 v201, v201, v98, v99
	v_max3_f32 v201, v201, v100, v101
	v_max3_f32 v201, v201, v102, v103
	v_max3_f32 v201, v201, v104, v105
	v_max3_f32 v201, v201, v106, v107
	v_max3_f32 v201, v201, v108, v109
	v_max3_f32 v201, v201, v110, v111
	v_max3_f32 v201, v201, v112, v113
	s_mov_b64 s[0:1], 0
